# attention q/k RMS-norm fused into the in-projection GEMM: each workgroup normalises the q/k tile it has just stored (same arithmetic), the separate pass in P2b is gone
# baseline (speedup 1.0000x reference)
; __device__ __forceinline__ unsigned cvt_pk_bf16(float lo, float hi) { unsigned r; asm volatile("v_cvt_pk_bf16_f32 %0, %1, %2" : "=v"(r) : "v"(lo), "v"(hi)); return r; }
; __device__ __forceinline__ float bflo(unsigned u) { return __uint_as_float(u << 16); }
;     __device__ __forceinline__ void operator()(const f32x4 (&acc)[2][2][4][2], const Unit& u, int wr, int wc, int fr, int fq) const {
;     ...
;             bf16_t* base; int ldc, c0; if (colt < 3072) { base = ZA; ldc = 3072; c0 = colt; } else { base = ZB; ldc = 5120; c0 = colt - 3072; }
; #pragma unroll
;             for (int ai = 0; ai < 2; ++ai)
; #pragma unroll
;                 for (int m = 0; m < 4; ++m) { bf16_t* rowp = base + (size_t)(row0 + ai * HALF + m * 16) * ldc + c0 + cl;
; #pragma unroll
;                     for (int bj = 0; bj < 2; ++bj) { const f32x4 v0 = acc[ai][bj][m][0], v1 = acc[ai][bj][m][1]; u32x4 w; w.x = cvt_pk_bf16(v0[0], v0[1]); w.y = cvt_pk_bf16(v0[2], v0[3]); w.z = cvt_pk_bf16(v1[0], v1[1]); w.w = cvt_pk_bf16(v1[2], v1[3]);
;                         *(u32x4*)(rowp + bj * HALF) = w; } }
; __device__ __forceinline__ void p2_qknorm_row(const Args& a, int row, int lane) {
;     bf16* zb = (bf16*)(a.ws + WS_ZB) + (size_t)row * 5120;
; #pragma unroll
;     for (int part = 0; part < 2; ++part) {
;         v4u* p = (v4u*)(zb + part * 1024 + lane * 16); const v4u u0 = p[0], u1 = p[1];
;         float x[16];
; #pragma unroll
;         for (int e = 0; e < 4; ++e) { x[2 * e] = bflo(u0[e]); x[2 * e + 1] = bfhi(u0[e]); x[8 + 2 * e] = bflo(u1[e]); x[8 + 2 * e + 1] = bfhi(u1[e]); }
;         float ss = 0.f;
; #pragma unroll
;         for (int e = 0; e < 16; ++e) ss += x[e] * x[e];
;         ss = quad_sum(ss);
;         const float rstd = (1.f / sqrtf(ss * (1.f / 64.f) + RMS_EPS)) * (part == 0 ? attn_body::C2 : 1.f);
;         const f32x4* g4 = (const f32x4*)(a.in[part == 0 ? 19 : 20] + (lane & 3) * 16);
;         v4u o0, o1;
; #pragma unroll
;         for (int e = 0; e < 2; ++e) { const f32x4 ga = g4[e], gb = g4[2 + e];
;             o0[2 * e] = pk2(x[4 * e] * rstd * ga.x, x[4 * e + 1] * rstd * ga.y); o0[2 * e + 1] = pk2(x[4 * e + 2] * rstd * ga.z, x[4 * e + 3] * rstd * ga.w);
;             o1[2 * e] = pk2(x[8 + 4 * e] * rstd * gb.x, x[8 + 4 * e + 1] * rstd * gb.y); o1[2 * e + 1] = pk2(x[8 + 4 * e + 2] * rstd * gb.z, x[8 + 4 * e + 3] * rstd * gb.w); }
.LBB0_194:
	s_lshl_b32 s3, s65, 8
	s_add_i32 s21, s3, 0xfffff400
	s_cmp_lt_i32 s65, 12
	s_movk_i32 s2, 0xc00
	s_cselect_b32 s40, s3, s21
	s_cselect_b32 s2, s2, 0x1400
	s_cselect_b32 s3, s73, s71
	s_cselect_b32 s21, s72, s70
	s_ashr_i32 s41, s40, 31
	s_lshl_b64 s[40:41], s[40:41], 1
	s_add_u32 s40, s21, s40
	s_addc_u32 s41, s3, s41
	v_lshl_add_u64 v[154:155], v[152:153], 1, s[40:41]
	v_mad_i64_i32 v[162:163], s[40:41], s2, v150, 0
	v_lshl_add_u64 v[166:167], v[162:163], 1, v[154:155]
	v_cvt_pk_bf16_f32 v162, v124, v125
	v_cvt_pk_bf16_f32 v163, v126, v127
	v_cvt_pk_bf16_f32 v164, v120, v121
	v_cvt_pk_bf16_f32 v165, v122, v123
	global_store_dwordx4 v[166:167], v[162:165], off
	v_add_u32_e32 v145, 0x80, v150
	s_nop 0
	v_cvt_pk_bf16_f32 v162, v108, v109
	v_cvt_pk_bf16_f32 v163, v110, v111
	v_cvt_pk_bf16_f32 v164, v100, v101
	v_cvt_pk_bf16_f32 v165, v102, v103
	global_store_dwordx4 v[166:167], v[162:165], off offset:256
	s_nop 1
	v_mad_i64_i32 v[162:163], s[40:41], s2, v148, 0
	v_lshl_add_u64 v[166:167], v[162:163], 1, v[154:155]
	v_cvt_pk_bf16_f32 v162, v116, v117
	v_cvt_pk_bf16_f32 v163, v118, v119
	v_cvt_pk_bf16_f32 v164, v112, v113
	v_cvt_pk_bf16_f32 v165, v114, v115
	global_store_dwordx4 v[166:167], v[162:165], off
	s_nop 1
	v_cvt_pk_bf16_f32 v162, v92, v93
	v_cvt_pk_bf16_f32 v163, v94, v95
	v_cvt_pk_bf16_f32 v164, v84, v85
	v_cvt_pk_bf16_f32 v165, v86, v87
	global_store_dwordx4 v[166:167], v[162:165], off offset:256
	s_nop 1
	v_mad_i64_i32 v[162:163], s[40:41], s2, v146, 0
	v_lshl_add_u64 v[166:167], v[162:163], 1, v[154:155]
	v_cvt_pk_bf16_f32 v162, v104, v105
	v_cvt_pk_bf16_f32 v163, v106, v107
	v_cvt_pk_bf16_f32 v164, v96, v97
	v_cvt_pk_bf16_f32 v165, v98, v99
	global_store_dwordx4 v[166:167], v[162:165], off
	s_nop 1
	v_cvt_pk_bf16_f32 v162, v76, v77
	v_cvt_pk_bf16_f32 v163, v78, v79
	v_cvt_pk_bf16_f32 v164, v72, v73
	v_cvt_pk_bf16_f32 v165, v74, v75
	global_store_dwordx4 v[166:167], v[162:165], off offset:256
	s_nop 1
	v_mad_i64_i32 v[162:163], s[40:41], s2, v144, 0
	v_lshl_add_u64 v[166:167], v[162:163], 1, v[154:155]
	v_cvt_pk_bf16_f32 v162, v88, v89
	v_cvt_pk_bf16_f32 v163, v90, v91
	v_cvt_pk_bf16_f32 v164, v80, v81
	v_cvt_pk_bf16_f32 v165, v82, v83
	global_store_dwordx4 v[166:167], v[162:165], off
	s_nop 1
	v_cvt_pk_bf16_f32 v162, v68, v69
	v_cvt_pk_bf16_f32 v163, v70, v71
	v_cvt_pk_bf16_f32 v164, v64, v65
	v_cvt_pk_bf16_f32 v165, v66, v67
	global_store_dwordx4 v[166:167], v[162:165], off offset:256
	s_nop 1
	v_mad_i64_i32 v[162:163], s[40:41], s2, v145, 0
	v_lshl_add_u64 v[166:167], v[162:163], 1, v[154:155]
	v_cvt_pk_bf16_f32 v162, v60, v61
	v_cvt_pk_bf16_f32 v163, v62, v63
	v_cvt_pk_bf16_f32 v164, v56, v57
	v_cvt_pk_bf16_f32 v165, v58, v59
	global_store_dwordx4 v[166:167], v[162:165], off
	v_add_u32_e32 v145, 0x90, v150
	s_nop 0
	v_cvt_pk_bf16_f32 v162, v44, v45
	v_cvt_pk_bf16_f32 v163, v46, v47
	v_cvt_pk_bf16_f32 v164, v40, v41
	v_cvt_pk_bf16_f32 v165, v42, v43
	global_store_dwordx4 v[166:167], v[162:165], off offset:256
	s_nop 1
	v_mad_i64_i32 v[162:163], s[40:41], s2, v145, 0
	v_lshl_add_u64 v[166:167], v[162:163], 1, v[154:155]
	v_cvt_pk_bf16_f32 v162, v52, v53
	v_cvt_pk_bf16_f32 v163, v54, v55
	v_cvt_pk_bf16_f32 v164, v48, v49
	v_cvt_pk_bf16_f32 v165, v50, v51
	global_store_dwordx4 v[166:167], v[162:165], off
	v_add_u32_e32 v145, 0xa0, v150
	s_nop 0
	v_cvt_pk_bf16_f32 v162, v28, v29
	v_cvt_pk_bf16_f32 v163, v30, v31
	v_cvt_pk_bf16_f32 v164, v24, v25
	v_cvt_pk_bf16_f32 v165, v26, v27
	global_store_dwordx4 v[166:167], v[162:165], off offset:256
	s_nop 1
	v_mad_i64_i32 v[162:163], s[40:41], s2, v145, 0
	v_lshl_add_u64 v[166:167], v[162:163], 1, v[154:155]
	v_cvt_pk_bf16_f32 v162, v36, v37
	v_cvt_pk_bf16_f32 v163, v38, v39
	v_cvt_pk_bf16_f32 v164, v32, v33
	v_cvt_pk_bf16_f32 v165, v34, v35
	global_store_dwordx4 v[166:167], v[162:165], off
	v_add_u32_e32 v145, 0xb0, v150
	s_nop 0
	v_cvt_pk_bf16_f32 v162, v12, v13
	v_cvt_pk_bf16_f32 v163, v14, v15
	v_cvt_pk_bf16_f32 v164, v8, v9
	v_cvt_pk_bf16_f32 v165, v10, v11
	global_store_dwordx4 v[166:167], v[162:165], off offset:256
	s_nop 1
	v_mad_i64_i32 v[162:163], s[2:3], s2, v145, 0
	v_lshl_add_u64 v[154:155], v[162:163], 1, v[154:155]
	v_cvt_pk_bf16_f32 v162, v20, v21
	v_cvt_pk_bf16_f32 v163, v22, v23
	v_cvt_pk_bf16_f32 v164, v16, v17
	v_cvt_pk_bf16_f32 v165, v18, v19
	global_store_dwordx4 v[154:155], v[162:165], off
	s_nop 1
	v_cvt_pk_bf16_f32 v162, v4, v5
	v_cvt_pk_bf16_f32 v163, v6, v7
	v_cvt_pk_bf16_f32 v164, v0, v1
	v_cvt_pk_bf16_f32 v165, v2, v3
	global_store_dwordx4 v[154:155], v[162:165], off offset:256
	s_cmp_lt_i32 s65, 12
	s_cbranch_scc1 .Lqkt_skip
	s_cmp_gt_i32 s65, 19
	s_cbranch_scc1 .Lqkt_skip
	s_waitcnt vmcnt(0)
	s_barrier
	v_mbcnt_lo_u32_b32 v10, -1, 0
	v_mbcnt_hi_u32_b32 v10, -1, v10
	s_lshl_b32 s100, s34, 8
	s_lshl_b32 s101, s92, 5
	s_add_i32 s100, s100, s101
	v_lshrrev_b32_e32 v11, 4, v10
	v_add_u32_e32 v11, s100, v11
	v_mul_u32_u24_e32 v6, 0x2800, v11
	v_mov_b32_e32 v7, 0
	s_lshl_b32 s100, s65, 9
	s_add_i32 s100, s100, 0xffffe800
	v_bfe_u32 v13, v10, 2, 2
	v_lshlrev_b32_e32 v13, 7, v13
	v_and_b32_e32 v14, 3, v10
	v_lshlrev_b32_e32 v15, 5, v14
	v_add3_u32 v13, v13, v15, s100
	v_add_u32_e32 v6, v6, v13
	v_add_u32_e32 v6, 0xf000000, v6
	v_lshl_add_u64 v[6:7], s[90:91], 0, v[6:7]
	v_lshlrev_b32_e32 v14, 6, v14
	v_mov_b32_e32 v15, 0
	s_cmp_lt_i32 s65, 16
	s_cbranch_scc0 .Lqkt_k
	v_readlane_b32 s100, v254, 12
	v_readlane_b32 s101, v254, 13
	s_nop 3
	v_mov_b32_e32 v2, s100
	v_mov_b32_e32 v3, s101
	s_mov_b32 s101, 0x3e38aa3b
	s_branch .Lqkt_w
.Lqkt_k:
	v_readlane_b32 s100, v254, 14
	v_readlane_b32 s101, v254, 15
	s_nop 3
	v_mov_b32_e32 v2, s100
	v_mov_b32_e32 v3, s101
	s_mov_b32 s101, 1.0
; __device__ __forceinline__ unsigned pk2(float lo, float hi) { f32x2_ v = {lo, hi}; return __builtin_bit_cast(unsigned, __builtin_convertvector(v, bf16x2_)); }
; __device__ __forceinline__ float bflo(unsigned u) { return __uint_as_float(u << 16); }
; __device__ __forceinline__ float bfhi(unsigned u) { return __uint_as_float(u & 0xffff0000u); }
; __device__ __forceinline__ void p2_qknorm_row(const Args& a, int row, int lane) {
;     bf16* zb = (bf16*)(a.ws + WS_ZB) + (size_t)row * 5120;
; #pragma unroll
;     for (int part = 0; part < 2; ++part) {
;         v4u* p = (v4u*)(zb + part * 1024 + lane * 16); const v4u u0 = p[0], u1 = p[1];
;         float x[16];
; #pragma unroll
;         for (int e = 0; e < 4; ++e) { x[2 * e] = bflo(u0[e]); x[2 * e + 1] = bfhi(u0[e]); x[8 + 2 * e] = bflo(u1[e]); x[8 + 2 * e + 1] = bfhi(u1[e]); }
;         float ss = 0.f;
; #pragma unroll
;         for (int e = 0; e < 16; ++e) ss += x[e] * x[e];
;         ss = quad_sum(ss);
;         const float rstd = (1.f / sqrtf(ss * (1.f / 64.f) + RMS_EPS)) * (part == 0 ? attn_body::C2 : 1.f);
;         const f32x4* g4 = (const f32x4*)(a.in[part == 0 ? 19 : 20] + (lane & 3) * 16);
;         v4u o0, o1;
; #pragma unroll
;         for (int e = 0; e < 2; ++e) { const f32x4 ga = g4[e], gb = g4[2 + e];
;             o0[2 * e] = pk2(x[4 * e] * rstd * ga.x, x[4 * e + 1] * rstd * ga.y); o0[2 * e + 1] = pk2(x[4 * e + 2] * rstd * ga.z, x[4 * e + 3] * rstd * ga.w);
;             o1[2 * e] = pk2(x[8 + 4 * e] * rstd * gb.x, x[8 + 4 * e + 1] * rstd * gb.y); o1[2 * e + 1] = pk2(x[8 + 4 * e + 2] * rstd * gb.z, x[8 + 4 * e + 3] * rstd * gb.w); }
;         p[0] = o0; p[1] = o1;
;     }
.Lqkt_w:
	v_lshl_add_u64 v[2:3], v[2:3], 0, v[14:15]
	global_load_dwordx4 v[110:113], v[2:3], off
	global_load_dwordx4 v[114:117], v[2:3], off offset:16
	global_load_dwordx4 v[118:121], v[2:3], off offset:32
	global_load_dwordx4 v[122:125], v[2:3], off offset:48
	v_mov_b32_e32 v1, 0x358637bd
	v_mov_b32_e32 v12, 0x260
	v_mov_b32_e32 v108, 0xa000
	v_mov_b32_e32 v109, 0
	v_mov_b32_e32 v126, 0x28000
	v_mov_b32_e32 v127, 0
	s_mov_b32 s100, 0
.Lqkt_batch:
	v_lshl_add_u64 v[2:3], v[6:7], 0, v[108:109]
	v_lshl_add_u64 v[4:5], v[2:3], 0, v[108:109]
	v_lshl_add_u64 v[8:9], v[4:5], 0, v[108:109]
	global_load_dwordx4 v[76:79], v[6:7], off
	global_load_dwordx4 v[80:83], v[6:7], off offset:16
	global_load_dwordx4 v[84:87], v[2:3], off
	global_load_dwordx4 v[88:91], v[2:3], off offset:16
	global_load_dwordx4 v[92:95], v[4:5], off
	global_load_dwordx4 v[96:99], v[4:5], off offset:16
	global_load_dwordx4 v[100:103], v[8:9], off
	global_load_dwordx4 v[104:107], v[8:9], off offset:16
	s_waitcnt vmcnt(0)
	v_mov_b32_e32 v18, v76
	v_mov_b32_e32 v19, v77
	v_mov_b32_e32 v20, v78
	v_mov_b32_e32 v21, v79
	v_mov_b32_e32 v14, v80
	v_mov_b32_e32 v15, v81
	v_mov_b32_e32 v16, v82
	v_mov_b32_e32 v17, v83
	v_lshlrev_b32_e32 v46, 16, v17
	v_lshlrev_b32_e32 v54, 16, v18
	v_and_b32_e32 v55, 0xffff0000, v18
	v_and_b32_e32 v47, 0xffff0000, v17
	v_lshlrev_b32_e32 v48, 16, v16
	v_and_b32_e32 v49, 0xffff0000, v16
	v_lshlrev_b32_e32 v16, 16, v21
	v_and_b32_e32 v17, 0xffff0000, v21
	v_lshlrev_b32_e32 v50, 16, v20
	v_and_b32_e32 v51, 0xffff0000, v20
	v_lshlrev_b32_e32 v20, 16, v15
	v_and_b32_e32 v21, 0xffff0000, v15
	v_lshlrev_b32_e32 v52, 16, v14
	v_and_b32_e32 v53, 0xffff0000, v14
	v_lshlrev_b32_e32 v14, 16, v19
	v_and_b32_e32 v15, 0xffff0000, v19
	v_pk_mul_f32 v[72:73], v[54:55], v[54:55]
	v_pk_mul_f32 v[70:71], v[14:15], v[14:15]
	v_add_f32_e32 v13, v72, v73
	v_add_f32_e32 v13, v70, v13
	v_pk_mul_f32 v[62:63], v[50:51], v[50:51]
	v_add_f32_e32 v13, v71, v13
	v_add_f32_e32 v13, v62, v13
	v_pk_mul_f32 v[60:61], v[16:17], v[16:17]
	v_add_f32_e32 v13, v63, v13
	v_add_f32_e32 v13, v60, v13
	v_pk_mul_f32 v[68:69], v[52:53], v[52:53]
	v_add_f32_e32 v13, v61, v13
	v_add_f32_e32 v13, v68, v13
	v_pk_mul_f32 v[66:67], v[20:21], v[20:21]
	v_add_f32_e32 v13, v69, v13
	v_add_f32_e32 v13, v66, v13
	v_pk_mul_f32 v[58:59], v[48:49], v[48:49]
	v_add_f32_e32 v13, v67, v13
	v_add_f32_e32 v13, v58, v13
	v_pk_mul_f32 v[18:19], v[46:47], v[46:47]
	v_add_f32_e32 v13, v59, v13
	v_add_f32_e32 v13, v18, v13
	v_add_f32_e32 v13, v19, v13
	s_nop 1
	v_add_f32_dpp v13, v13, v13 quad_perm:[1,0,3,2] row_mask:0xf bank_mask:0xf bound_ctrl:1
	s_nop 1
	v_add_f32_dpp v13, v13, v13 quad_perm:[2,3,0,1] row_mask:0xf bank_mask:0xf bound_ctrl:1
	v_fmamk_f32 v13, v13, 0x3c800000, v1
	v_mul_f32_e32 v18, 0x4f800000, v13
	v_cmp_gt_f32_e32 vcc, 0xf800000, v13
	s_nop 1
	v_cndmask_b32_e32 v13, v13, v18, vcc
	v_sqrt_f32_e32 v18, v13
	s_nop 0
	v_add_u32_e32 v19, -1, v18
	v_add_u32_e32 v29, 1, v18
	v_fma_f32 v58, -v19, v18, v13
	v_fma_f32 v59, -v29, v18, v13
	v_cmp_ge_f32_e64 s[98:99], 0, v58
	s_nop 1
	v_cndmask_b32_e64 v18, v18, v19, s[98:99]
	v_cmp_lt_f32_e64 s[98:99], 0, v59
	s_nop 1
	v_cndmask_b32_e64 v18, v18, v29, s[98:99]
	v_mul_f32_e32 v19, 0x37800000, v18
	v_cndmask_b32_e32 v18, v18, v19, vcc
	v_cmp_class_f32_e32 vcc, v13, v12
	s_nop 1
	v_cndmask_b32_e32 v13, v18, v13, vcc
	v_div_scale_f32 v18, s[98:99], v13, v13, 1.0
	v_rcp_f32_e32 v19, v18
	v_div_scale_f32 v29, vcc, 1.0, v13, 1.0
	v_fma_f32 v59, -v18, v19, 1.0
	v_fmac_f32_e32 v19, v59, v19
	v_mul_f32_e32 v59, v29, v19
	v_fma_f32 v60, -v18, v59, v29
	v_fmac_f32_e32 v59, v60, v19
	v_fma_f32 v18, -v18, v59, v29
	v_div_fmas_f32 v18, v18, v19, v59
	v_div_fixup_f32 v13, v18, v13, 1.0
	v_mul_f32_e32 v18, s101, v13
	v_pk_mul_f32 v[54:55], v[18:19], v[54:55] op_sel_hi:[0,1]
	v_pk_mul_f32 v[14:15], v[18:19], v[14:15] op_sel_hi:[0,1]
	v_pk_mul_f32 v[20:21], v[18:19], v[20:21] op_sel_hi:[0,1]
	v_pk_mul_f32 v[50:51], v[18:19], v[50:51] op_sel_hi:[0,1]
	v_pk_mul_f32 v[16:17], v[18:19], v[16:17] op_sel_hi:[0,1]
	v_pk_mul_f32 v[52:53], v[18:19], v[52:53] op_sel_hi:[0,1]
	v_pk_mul_f32 v[48:49], v[18:19], v[48:49] op_sel_hi:[0,1]
	v_pk_mul_f32 v[18:19], v[18:19], v[46:47] op_sel_hi:[0,1]
	v_pk_mul_f32 v[42:43], v[110:111], v[54:55]
	v_pk_mul_f32 v[44:45], v[112:113], v[14:15]
	v_pk_mul_f32 v[20:21], v[120:121], v[20:21]
	v_pk_mul_f32 v[36:37], v[114:115], v[50:51]
	v_pk_mul_f32 v[38:39], v[116:117], v[16:17]
	v_pk_mul_f32 v[34:35], v[118:119], v[52:53]
	v_pk_mul_f32 v[30:31], v[122:123], v[48:49]
	v_pk_mul_f32 v[32:33], v[124:125], v[18:19]
	v_cvt_pk_bf16_f32 v14, v42, v43
	v_cvt_pk_bf16_f32 v15, v44, v45
	v_cvt_pk_bf16_f32 v16, v36, v37
	v_cvt_pk_bf16_f32 v17, v38, v39
	v_cvt_pk_bf16_f32 v18, v34, v35
	v_cvt_pk_bf16_f32 v19, v20, v21
	v_cvt_pk_bf16_f32 v20, v30, v31
	v_cvt_pk_bf16_f32 v21, v32, v33
	global_store_dwordx4 v[6:7], v[14:17], off
	global_store_dwordx4 v[6:7], v[18:21], off offset:16
	s_nop 1
	v_mov_b32_e32 v18, v84
	v_mov_b32_e32 v19, v85
	v_mov_b32_e32 v20, v86
	v_mov_b32_e32 v21, v87
	v_mov_b32_e32 v14, v88
	v_mov_b32_e32 v15, v89
	v_mov_b32_e32 v16, v90
	v_mov_b32_e32 v17, v91
	v_lshlrev_b32_e32 v46, 16, v17
	v_lshlrev_b32_e32 v54, 16, v18
	v_and_b32_e32 v55, 0xffff0000, v18
	v_and_b32_e32 v47, 0xffff0000, v17
	v_lshlrev_b32_e32 v48, 16, v16
	v_and_b32_e32 v49, 0xffff0000, v16
	v_lshlrev_b32_e32 v16, 16, v21
	v_and_b32_e32 v17, 0xffff0000, v21
	v_lshlrev_b32_e32 v50, 16, v20
	v_and_b32_e32 v51, 0xffff0000, v20
	v_lshlrev_b32_e32 v20, 16, v15
	v_and_b32_e32 v21, 0xffff0000, v15
	v_lshlrev_b32_e32 v52, 16, v14
	v_and_b32_e32 v53, 0xffff0000, v14
	v_lshlrev_b32_e32 v14, 16, v19
; __device__ __forceinline__ unsigned pk2(float lo, float hi) { f32x2_ v = {lo, hi}; return __builtin_bit_cast(unsigned, __builtin_convertvector(v, bf16x2_)); }
; __device__ __forceinline__ float bflo(unsigned u) { return __uint_as_float(u << 16); }
; __device__ __forceinline__ float bfhi(unsigned u) { return __uint_as_float(u & 0xffff0000u); }
; __device__ __forceinline__ void p2_qknorm_row(const Args& a, int row, int lane) {
;     bf16* zb = (bf16*)(a.ws + WS_ZB) + (size_t)row * 5120;
; #pragma unroll
;     for (int part = 0; part < 2; ++part) {
;         v4u* p = (v4u*)(zb + part * 1024 + lane * 16); const v4u u0 = p[0], u1 = p[1];
;         float x[16];
; #pragma unroll
;         for (int e = 0; e < 4; ++e) { x[2 * e] = bflo(u0[e]); x[2 * e + 1] = bfhi(u0[e]); x[8 + 2 * e] = bflo(u1[e]); x[8 + 2 * e + 1] = bfhi(u1[e]); }
;         float ss = 0.f;
; #pragma unroll
;         for (int e = 0; e < 16; ++e) ss += x[e] * x[e];
;         ss = quad_sum(ss);
;         const float rstd = (1.f / sqrtf(ss * (1.f / 64.f) + RMS_EPS)) * (part == 0 ? attn_body::C2 : 1.f);
;         const f32x4* g4 = (const f32x4*)(a.in[part == 0 ? 19 : 20] + (lane & 3) * 16);
;         v4u o0, o1;
; #pragma unroll
;         for (int e = 0; e < 2; ++e) { const f32x4 ga = g4[e], gb = g4[2 + e];
;             o0[2 * e] = pk2(x[4 * e] * rstd * ga.x, x[4 * e + 1] * rstd * ga.y); o0[2 * e + 1] = pk2(x[4 * e + 2] * rstd * ga.z, x[4 * e + 3] * rstd * ga.w);
;             o1[2 * e] = pk2(x[8 + 4 * e] * rstd * gb.x, x[8 + 4 * e + 1] * rstd * gb.y); o1[2 * e + 1] = pk2(x[8 + 4 * e + 2] * rstd * gb.z, x[8 + 4 * e + 3] * rstd * gb.w); }
;         p[0] = o0; p[1] = o1;
;     }
	v_and_b32_e32 v15, 0xffff0000, v19
	v_pk_mul_f32 v[72:73], v[54:55], v[54:55]
	v_pk_mul_f32 v[70:71], v[14:15], v[14:15]
	v_add_f32_e32 v13, v72, v73
	v_add_f32_e32 v13, v70, v13
	v_pk_mul_f32 v[62:63], v[50:51], v[50:51]
	v_add_f32_e32 v13, v71, v13
	v_add_f32_e32 v13, v62, v13
	v_pk_mul_f32 v[60:61], v[16:17], v[16:17]
	v_add_f32_e32 v13, v63, v13
	v_add_f32_e32 v13, v60, v13
	v_pk_mul_f32 v[68:69], v[52:53], v[52:53]
	v_add_f32_e32 v13, v61, v13
	v_add_f32_e32 v13, v68, v13
	v_pk_mul_f32 v[66:67], v[20:21], v[20:21]
	v_add_f32_e32 v13, v69, v13
	v_add_f32_e32 v13, v66, v13
	v_pk_mul_f32 v[58:59], v[48:49], v[48:49]
	v_add_f32_e32 v13, v67, v13
	v_add_f32_e32 v13, v58, v13
	v_pk_mul_f32 v[18:19], v[46:47], v[46:47]
	v_add_f32_e32 v13, v59, v13
	v_add_f32_e32 v13, v18, v13
	v_add_f32_e32 v13, v19, v13
	s_nop 1
	v_add_f32_dpp v13, v13, v13 quad_perm:[1,0,3,2] row_mask:0xf bank_mask:0xf bound_ctrl:1
	s_nop 1
	v_add_f32_dpp v13, v13, v13 quad_perm:[2,3,0,1] row_mask:0xf bank_mask:0xf bound_ctrl:1
	v_fmamk_f32 v13, v13, 0x3c800000, v1
	v_mul_f32_e32 v18, 0x4f800000, v13
	v_cmp_gt_f32_e32 vcc, 0xf800000, v13
	s_nop 1
	v_cndmask_b32_e32 v13, v13, v18, vcc
	v_sqrt_f32_e32 v18, v13
	s_nop 0
	v_add_u32_e32 v19, -1, v18
	v_add_u32_e32 v29, 1, v18
	v_fma_f32 v58, -v19, v18, v13
	v_fma_f32 v59, -v29, v18, v13
	v_cmp_ge_f32_e64 s[98:99], 0, v58
	s_nop 1
	v_cndmask_b32_e64 v18, v18, v19, s[98:99]
	v_cmp_lt_f32_e64 s[98:99], 0, v59
	s_nop 1
	v_cndmask_b32_e64 v18, v18, v29, s[98:99]
	v_mul_f32_e32 v19, 0x37800000, v18
	v_cndmask_b32_e32 v18, v18, v19, vcc
	v_cmp_class_f32_e32 vcc, v13, v12
	s_nop 1
	v_cndmask_b32_e32 v13, v18, v13, vcc
	v_div_scale_f32 v18, s[98:99], v13, v13, 1.0
	v_rcp_f32_e32 v19, v18
	v_div_scale_f32 v29, vcc, 1.0, v13, 1.0
	v_fma_f32 v59, -v18, v19, 1.0
	v_fmac_f32_e32 v19, v59, v19
	v_mul_f32_e32 v59, v29, v19
	v_fma_f32 v60, -v18, v59, v29
	v_fmac_f32_e32 v59, v60, v19
	v_fma_f32 v18, -v18, v59, v29
	v_div_fmas_f32 v18, v18, v19, v59
	v_div_fixup_f32 v13, v18, v13, 1.0
	v_mul_f32_e32 v18, s101, v13
	v_pk_mul_f32 v[54:55], v[18:19], v[54:55] op_sel_hi:[0,1]
	v_pk_mul_f32 v[14:15], v[18:19], v[14:15] op_sel_hi:[0,1]
	v_pk_mul_f32 v[20:21], v[18:19], v[20:21] op_sel_hi:[0,1]
	v_pk_mul_f32 v[50:51], v[18:19], v[50:51] op_sel_hi:[0,1]
	v_pk_mul_f32 v[16:17], v[18:19], v[16:17] op_sel_hi:[0,1]
	v_pk_mul_f32 v[52:53], v[18:19], v[52:53] op_sel_hi:[0,1]
	v_pk_mul_f32 v[48:49], v[18:19], v[48:49] op_sel_hi:[0,1]
	v_pk_mul_f32 v[18:19], v[18:19], v[46:47] op_sel_hi:[0,1]
	v_pk_mul_f32 v[42:43], v[110:111], v[54:55]
	v_pk_mul_f32 v[44:45], v[112:113], v[14:15]
	v_pk_mul_f32 v[20:21], v[120:121], v[20:21]
	v_pk_mul_f32 v[36:37], v[114:115], v[50:51]
	v_pk_mul_f32 v[38:39], v[116:117], v[16:17]
	v_pk_mul_f32 v[34:35], v[118:119], v[52:53]
	v_pk_mul_f32 v[30:31], v[122:123], v[48:49]
	v_pk_mul_f32 v[32:33], v[124:125], v[18:19]
	v_cvt_pk_bf16_f32 v14, v42, v43
	v_cvt_pk_bf16_f32 v15, v44, v45
	v_cvt_pk_bf16_f32 v16, v36, v37
	v_cvt_pk_bf16_f32 v17, v38, v39
	v_cvt_pk_bf16_f32 v18, v34, v35
	v_cvt_pk_bf16_f32 v19, v20, v21
	v_cvt_pk_bf16_f32 v20, v30, v31
	v_cvt_pk_bf16_f32 v21, v32, v33
	global_store_dwordx4 v[2:3], v[14:17], off
	global_store_dwordx4 v[2:3], v[18:21], off offset:16
	s_nop 1
	v_mov_b32_e32 v18, v92
	v_mov_b32_e32 v19, v93
	v_mov_b32_e32 v20, v94
	v_mov_b32_e32 v21, v95
	v_mov_b32_e32 v14, v96
	v_mov_b32_e32 v15, v97
	v_mov_b32_e32 v16, v98
	v_mov_b32_e32 v17, v99
	v_lshlrev_b32_e32 v46, 16, v17
	v_lshlrev_b32_e32 v54, 16, v18
	v_and_b32_e32 v55, 0xffff0000, v18
	v_and_b32_e32 v47, 0xffff0000, v17
	v_lshlrev_b32_e32 v48, 16, v16
	v_and_b32_e32 v49, 0xffff0000, v16
	v_lshlrev_b32_e32 v16, 16, v21
	v_and_b32_e32 v17, 0xffff0000, v21
	v_lshlrev_b32_e32 v50, 16, v20
	v_and_b32_e32 v51, 0xffff0000, v20
	v_lshlrev_b32_e32 v20, 16, v15
	v_and_b32_e32 v21, 0xffff0000, v15
	v_lshlrev_b32_e32 v52, 16, v14
	v_and_b32_e32 v53, 0xffff0000, v14
	v_lshlrev_b32_e32 v14, 16, v19
	v_and_b32_e32 v15, 0xffff0000, v19
	v_pk_mul_f32 v[72:73], v[54:55], v[54:55]
	v_pk_mul_f32 v[70:71], v[14:15], v[14:15]
	v_add_f32_e32 v13, v72, v73
	v_add_f32_e32 v13, v70, v13
	v_pk_mul_f32 v[62:63], v[50:51], v[50:51]
	v_add_f32_e32 v13, v71, v13
	v_add_f32_e32 v13, v62, v13
	v_pk_mul_f32 v[60:61], v[16:17], v[16:17]
	v_add_f32_e32 v13, v63, v13
	v_add_f32_e32 v13, v60, v13
	v_pk_mul_f32 v[68:69], v[52:53], v[52:53]
	v_add_f32_e32 v13, v61, v13
	v_add_f32_e32 v13, v68, v13
	v_pk_mul_f32 v[66:67], v[20:21], v[20:21]
	v_add_f32_e32 v13, v69, v13
	v_add_f32_e32 v13, v66, v13
	v_pk_mul_f32 v[58:59], v[48:49], v[48:49]
	v_add_f32_e32 v13, v67, v13
	v_add_f32_e32 v13, v58, v13
	v_pk_mul_f32 v[18:19], v[46:47], v[46:47]
	v_add_f32_e32 v13, v59, v13
	v_add_f32_e32 v13, v18, v13
	v_add_f32_e32 v13, v19, v13
	s_nop 1
	v_add_f32_dpp v13, v13, v13 quad_perm:[1,0,3,2] row_mask:0xf bank_mask:0xf bound_ctrl:1
	s_nop 1
	v_add_f32_dpp v13, v13, v13 quad_perm:[2,3,0,1] row_mask:0xf bank_mask:0xf bound_ctrl:1
	v_fmamk_f32 v13, v13, 0x3c800000, v1
	v_mul_f32_e32 v18, 0x4f800000, v13
	v_cmp_gt_f32_e32 vcc, 0xf800000, v13
	s_nop 1
	v_cndmask_b32_e32 v13, v13, v18, vcc
	v_sqrt_f32_e32 v18, v13
	s_nop 0
	v_add_u32_e32 v19, -1, v18
	v_add_u32_e32 v29, 1, v18
	v_fma_f32 v58, -v19, v18, v13
	v_fma_f32 v59, -v29, v18, v13
	v_cmp_ge_f32_e64 s[98:99], 0, v58
	s_nop 1
	v_cndmask_b32_e64 v18, v18, v19, s[98:99]
	v_cmp_lt_f32_e64 s[98:99], 0, v59
	s_nop 1
	v_cndmask_b32_e64 v18, v18, v29, s[98:99]
	v_mul_f32_e32 v19, 0x37800000, v18
	v_cndmask_b32_e32 v18, v18, v19, vcc
	v_cmp_class_f32_e32 vcc, v13, v12
	s_nop 1
	v_cndmask_b32_e32 v13, v18, v13, vcc
	v_div_scale_f32 v18, s[98:99], v13, v13, 1.0
; __device__ __forceinline__ unsigned pk2(float lo, float hi) { f32x2_ v = {lo, hi}; return __builtin_bit_cast(unsigned, __builtin_convertvector(v, bf16x2_)); }
; __device__ __forceinline__ float bflo(unsigned u) { return __uint_as_float(u << 16); }
; __device__ __forceinline__ float bfhi(unsigned u) { return __uint_as_float(u & 0xffff0000u); }
; __device__ __forceinline__ void p2_qknorm_row(const Args& a, int row, int lane) {
;     bf16* zb = (bf16*)(a.ws + WS_ZB) + (size_t)row * 5120;
; #pragma unroll
;     for (int part = 0; part < 2; ++part) {
;         v4u* p = (v4u*)(zb + part * 1024 + lane * 16); const v4u u0 = p[0], u1 = p[1];
;         float x[16];
; #pragma unroll
;         for (int e = 0; e < 4; ++e) { x[2 * e] = bflo(u0[e]); x[2 * e + 1] = bfhi(u0[e]); x[8 + 2 * e] = bflo(u1[e]); x[8 + 2 * e + 1] = bfhi(u1[e]); }
;         float ss = 0.f;
; #pragma unroll
;         for (int e = 0; e < 16; ++e) ss += x[e] * x[e];
;         ss = quad_sum(ss);
;         const float rstd = (1.f / sqrtf(ss * (1.f / 64.f) + RMS_EPS)) * (part == 0 ? attn_body::C2 : 1.f);
;         const f32x4* g4 = (const f32x4*)(a.in[part == 0 ? 19 : 20] + (lane & 3) * 16);
;         v4u o0, o1;
; #pragma unroll
;         for (int e = 0; e < 2; ++e) { const f32x4 ga = g4[e], gb = g4[2 + e];
;             o0[2 * e] = pk2(x[4 * e] * rstd * ga.x, x[4 * e + 1] * rstd * ga.y); o0[2 * e + 1] = pk2(x[4 * e + 2] * rstd * ga.z, x[4 * e + 3] * rstd * ga.w);
;             o1[2 * e] = pk2(x[8 + 4 * e] * rstd * gb.x, x[8 + 4 * e + 1] * rstd * gb.y); o1[2 * e + 1] = pk2(x[8 + 4 * e + 2] * rstd * gb.z, x[8 + 4 * e + 3] * rstd * gb.w); }
;         p[0] = o0; p[1] = o1;
;     }
	v_rcp_f32_e32 v19, v18
	v_div_scale_f32 v29, vcc, 1.0, v13, 1.0
	v_fma_f32 v59, -v18, v19, 1.0
	v_fmac_f32_e32 v19, v59, v19
	v_mul_f32_e32 v59, v29, v19
	v_fma_f32 v60, -v18, v59, v29
	v_fmac_f32_e32 v59, v60, v19
	v_fma_f32 v18, -v18, v59, v29
	v_div_fmas_f32 v18, v18, v19, v59
	v_div_fixup_f32 v13, v18, v13, 1.0
	v_mul_f32_e32 v18, s101, v13
	v_pk_mul_f32 v[54:55], v[18:19], v[54:55] op_sel_hi:[0,1]
	v_pk_mul_f32 v[14:15], v[18:19], v[14:15] op_sel_hi:[0,1]
	v_pk_mul_f32 v[20:21], v[18:19], v[20:21] op_sel_hi:[0,1]
	v_pk_mul_f32 v[50:51], v[18:19], v[50:51] op_sel_hi:[0,1]
	v_pk_mul_f32 v[16:17], v[18:19], v[16:17] op_sel_hi:[0,1]
	v_pk_mul_f32 v[52:53], v[18:19], v[52:53] op_sel_hi:[0,1]
	v_pk_mul_f32 v[48:49], v[18:19], v[48:49] op_sel_hi:[0,1]
	v_pk_mul_f32 v[18:19], v[18:19], v[46:47] op_sel_hi:[0,1]
	v_pk_mul_f32 v[42:43], v[110:111], v[54:55]
	v_pk_mul_f32 v[44:45], v[112:113], v[14:15]
	v_pk_mul_f32 v[20:21], v[120:121], v[20:21]
	v_pk_mul_f32 v[36:37], v[114:115], v[50:51]
	v_pk_mul_f32 v[38:39], v[116:117], v[16:17]
	v_pk_mul_f32 v[34:35], v[118:119], v[52:53]
	v_pk_mul_f32 v[30:31], v[122:123], v[48:49]
	v_pk_mul_f32 v[32:33], v[124:125], v[18:19]
	v_cvt_pk_bf16_f32 v14, v42, v43
	v_cvt_pk_bf16_f32 v15, v44, v45
	v_cvt_pk_bf16_f32 v16, v36, v37
	v_cvt_pk_bf16_f32 v17, v38, v39
	v_cvt_pk_bf16_f32 v18, v34, v35
	v_cvt_pk_bf16_f32 v19, v20, v21
	v_cvt_pk_bf16_f32 v20, v30, v31
	v_cvt_pk_bf16_f32 v21, v32, v33
	global_store_dwordx4 v[4:5], v[14:17], off
	global_store_dwordx4 v[4:5], v[18:21], off offset:16
	s_nop 1
	v_mov_b32_e32 v18, v100
	v_mov_b32_e32 v19, v101
	v_mov_b32_e32 v20, v102
	v_mov_b32_e32 v21, v103
	v_mov_b32_e32 v14, v104
	v_mov_b32_e32 v15, v105
	v_mov_b32_e32 v16, v106
	v_mov_b32_e32 v17, v107
	v_lshlrev_b32_e32 v46, 16, v17
	v_lshlrev_b32_e32 v54, 16, v18
	v_and_b32_e32 v55, 0xffff0000, v18
	v_and_b32_e32 v47, 0xffff0000, v17
	v_lshlrev_b32_e32 v48, 16, v16
	v_and_b32_e32 v49, 0xffff0000, v16
	v_lshlrev_b32_e32 v16, 16, v21
	v_and_b32_e32 v17, 0xffff0000, v21
	v_lshlrev_b32_e32 v50, 16, v20
	v_and_b32_e32 v51, 0xffff0000, v20
	v_lshlrev_b32_e32 v20, 16, v15
	v_and_b32_e32 v21, 0xffff0000, v15
	v_lshlrev_b32_e32 v52, 16, v14
	v_and_b32_e32 v53, 0xffff0000, v14
	v_lshlrev_b32_e32 v14, 16, v19
	v_and_b32_e32 v15, 0xffff0000, v19
	v_pk_mul_f32 v[72:73], v[54:55], v[54:55]
	v_pk_mul_f32 v[70:71], v[14:15], v[14:15]
	v_add_f32_e32 v13, v72, v73
	v_add_f32_e32 v13, v70, v13
	v_pk_mul_f32 v[62:63], v[50:51], v[50:51]
	v_add_f32_e32 v13, v71, v13
	v_add_f32_e32 v13, v62, v13
	v_pk_mul_f32 v[60:61], v[16:17], v[16:17]
	v_add_f32_e32 v13, v63, v13
	v_add_f32_e32 v13, v60, v13
	v_pk_mul_f32 v[68:69], v[52:53], v[52:53]
	v_add_f32_e32 v13, v61, v13
	v_add_f32_e32 v13, v68, v13
	v_pk_mul_f32 v[66:67], v[20:21], v[20:21]
	v_add_f32_e32 v13, v69, v13
	v_add_f32_e32 v13, v66, v13
	v_pk_mul_f32 v[58:59], v[48:49], v[48:49]
	v_add_f32_e32 v13, v67, v13
	v_add_f32_e32 v13, v58, v13
	v_pk_mul_f32 v[18:19], v[46:47], v[46:47]
	v_add_f32_e32 v13, v59, v13
	v_add_f32_e32 v13, v18, v13
	v_add_f32_e32 v13, v19, v13
	s_nop 1
	v_add_f32_dpp v13, v13, v13 quad_perm:[1,0,3,2] row_mask:0xf bank_mask:0xf bound_ctrl:1
	s_nop 1
	v_add_f32_dpp v13, v13, v13 quad_perm:[2,3,0,1] row_mask:0xf bank_mask:0xf bound_ctrl:1
	v_fmamk_f32 v13, v13, 0x3c800000, v1
	v_mul_f32_e32 v18, 0x4f800000, v13
	v_cmp_gt_f32_e32 vcc, 0xf800000, v13
	s_nop 1
	v_cndmask_b32_e32 v13, v13, v18, vcc
	v_sqrt_f32_e32 v18, v13
	s_nop 0
	v_add_u32_e32 v19, -1, v18
	v_add_u32_e32 v29, 1, v18
	v_fma_f32 v58, -v19, v18, v13
	v_fma_f32 v59, -v29, v18, v13
	v_cmp_ge_f32_e64 s[98:99], 0, v58
	s_nop 1
	v_cndmask_b32_e64 v18, v18, v19, s[98:99]
	v_cmp_lt_f32_e64 s[98:99], 0, v59
	s_nop 1
	v_cndmask_b32_e64 v18, v18, v29, s[98:99]
	v_mul_f32_e32 v19, 0x37800000, v18
	v_cndmask_b32_e32 v18, v18, v19, vcc
	v_cmp_class_f32_e32 vcc, v13, v12
	s_nop 1
	v_cndmask_b32_e32 v13, v18, v13, vcc
	v_div_scale_f32 v18, s[98:99], v13, v13, 1.0
	v_rcp_f32_e32 v19, v18
	v_div_scale_f32 v29, vcc, 1.0, v13, 1.0
	v_fma_f32 v59, -v18, v19, 1.0
	v_fmac_f32_e32 v19, v59, v19
	v_mul_f32_e32 v59, v29, v19
	v_fma_f32 v60, -v18, v59, v29
	v_fmac_f32_e32 v59, v60, v19
	v_fma_f32 v18, -v18, v59, v29
	v_div_fmas_f32 v18, v18, v19, v59
	v_div_fixup_f32 v13, v18, v13, 1.0
	v_mul_f32_e32 v18, s101, v13
	v_pk_mul_f32 v[54:55], v[18:19], v[54:55] op_sel_hi:[0,1]
	v_pk_mul_f32 v[14:15], v[18:19], v[14:15] op_sel_hi:[0,1]
	v_pk_mul_f32 v[20:21], v[18:19], v[20:21] op_sel_hi:[0,1]
	v_pk_mul_f32 v[50:51], v[18:19], v[50:51] op_sel_hi:[0,1]
	v_pk_mul_f32 v[16:17], v[18:19], v[16:17] op_sel_hi:[0,1]
	v_pk_mul_f32 v[52:53], v[18:19], v[52:53] op_sel_hi:[0,1]
	v_pk_mul_f32 v[48:49], v[18:19], v[48:49] op_sel_hi:[0,1]
	v_pk_mul_f32 v[18:19], v[18:19], v[46:47] op_sel_hi:[0,1]
	v_pk_mul_f32 v[42:43], v[110:111], v[54:55]
	v_pk_mul_f32 v[44:45], v[112:113], v[14:15]
	v_pk_mul_f32 v[20:21], v[120:121], v[20:21]
	v_pk_mul_f32 v[36:37], v[114:115], v[50:51]
	v_pk_mul_f32 v[38:39], v[116:117], v[16:17]
	v_pk_mul_f32 v[34:35], v[118:119], v[52:53]
	v_pk_mul_f32 v[30:31], v[122:123], v[48:49]
	v_pk_mul_f32 v[32:33], v[124:125], v[18:19]
	v_cvt_pk_bf16_f32 v14, v42, v43
	v_cvt_pk_bf16_f32 v15, v44, v45
	v_cvt_pk_bf16_f32 v16, v36, v37
	v_cvt_pk_bf16_f32 v17, v38, v39
	v_cvt_pk_bf16_f32 v18, v34, v35
	v_cvt_pk_bf16_f32 v19, v20, v21
	v_cvt_pk_bf16_f32 v20, v30, v31
	v_cvt_pk_bf16_f32 v21, v32, v33
	global_store_dwordx4 v[8:9], v[14:17], off
	global_store_dwordx4 v[8:9], v[18:21], off offset:16
	s_nop 1
	v_lshl_add_u64 v[6:7], v[6:7], 0, v[126:127]
	s_add_i32 s100, s100, 1
	s_cmp_lt_u32 s100, 2
	s_cbranch_scc1 .Lqkt_batch
	s_waitcnt vmcnt(0)
;     __device__ __forceinline__ void operator()(const f32x4 (&acc)[2][2][4][2], const Unit& u, int wr, int wc, int fr, int fq) const {
;     ...
;         if (colt >= 8192) {
; #pragma unroll
;             for (int ai = 0; ai < 2; ++ai)
; #pragma unroll
;                 for (int m = 0; m < 4; ++m) { float* rowp = ZS + (size_t)(row0 + ai * HALF + m * 16) * 256 + cl;
; #pragma unroll
;                     for (int bj = 0; bj < 2; ++bj) { *(f32x4*)(rowp + bj * HALF) = acc[ai][bj][m][0]; *(f32x4*)(rowp + bj * HALF + 4) = acc[ai][bj][m][1]; } }
.Lqkt_skip:
	s_cbranch_execnz .LBB0_193
.LBB0_195:
	v_ashrrev_i32_e32 v151, 31, v150
	v_lshlrev_b64 v[150:151], 10, v[150:151]
	v_lshl_add_u64 v[150:151], s[14:15], 0, v[150:151]
	v_lshlrev_b64 v[152:153], 2, v[152:153]
	v_lshl_add_u64 v[150:151], v[150:151], 0, v[152:153]
	v_ashrrev_i32_e32 v149, 31, v148
	global_store_dwordx4 v[150:151], v[124:127], off
	global_store_dwordx4 v[150:151], v[120:123], off offset:16
	global_store_dwordx4 v[150:151], v[108:111], off offset:512
	global_store_dwordx4 v[150:151], v[100:103], off offset:528
	v_ashrrev_i32_e32 v147, 31, v146
	v_ashrrev_i32_e32 v145, 31, v144
	v_lshlrev_b64 v[100:101], 10, v[148:149]
	v_lshl_add_u64 v[100:101], s[14:15], 0, v[100:101]
	v_lshl_add_u64 v[100:101], v[100:101], 0, v[152:153]
	global_store_dwordx4 v[100:101], v[116:119], off
	global_store_dwordx4 v[100:101], v[112:115], off offset:16
	global_store_dwordx4 v[100:101], v[92:95], off offset:512
	global_store_dwordx4 v[100:101], v[84:87], off offset:528
	s_mov_b64 s[2:3], 0x20000
	s_nop 0
	v_lshlrev_b64 v[84:85], 10, v[146:147]
	v_lshl_add_u64 v[84:85], s[14:15], 0, v[84:85]
	v_lshl_add_u64 v[84:85], v[84:85], 0, v[152:153]
	global_store_dwordx4 v[84:85], v[104:107], off
	global_store_dwordx4 v[84:85], v[96:99], off offset:16
	global_store_dwordx4 v[84:85], v[76:79], off offset:512
	global_store_dwordx4 v[84:85], v[72:75], off offset:528
	s_nop 1
	v_lshlrev_b64 v[72:73], 10, v[144:145]
	v_lshl_add_u64 v[72:73], s[14:15], 0, v[72:73]
	v_lshl_add_u64 v[72:73], v[72:73], 0, v[152:153]
	global_store_dwordx4 v[72:73], v[88:91], off
	global_store_dwordx4 v[72:73], v[80:83], off offset:16
	global_store_dwordx4 v[72:73], v[68:71], off offset:512
	global_store_dwordx4 v[72:73], v[64:67], off offset:528
	s_nop 1
	v_lshl_add_u64 v[64:65], v[150:151], 0, s[2:3]
	s_mov_b32 s2, 0x20000
	v_add_co_u32_e32 v66, vcc, s2, v150
	s_mov_b64 s[2:3], 0x24000
	s_nop 0
	v_addc_co_u32_e32 v67, vcc, 0, v151, vcc
	global_store_dwordx4 v[66:67], v[60:63], off
	global_store_dwordx4 v[64:65], v[56:59], off offset:16
	global_store_dwordx4 v[64:65], v[44:47], off offset:512
	global_store_dwordx4 v[64:65], v[40:43], off offset:528
	s_nop 1
	v_lshl_add_u64 v[40:41], v[150:151], 0, s[2:3]
	s_mov_b32 s2, 0x24000
	v_add_co_u32_e32 v42, vcc, s2, v150
	s_mov_b64 s[2:3], 0x28000
	s_nop 0
	v_addc_co_u32_e32 v43, vcc, 0, v151, vcc
	global_store_dwordx4 v[42:43], v[52:55], off
	global_store_dwordx4 v[40:41], v[48:51], off offset:16
	global_store_dwordx4 v[40:41], v[28:31], off offset:512
	global_store_dwordx4 v[40:41], v[24:27], off offset:528
	s_nop 1
	v_add_co_u32_e32 v26, vcc, 0x28000, v150
	v_lshl_add_u64 v[24:25], v[150:151], 0, s[2:3]
	s_nop 0
	v_addc_co_u32_e32 v27, vcc, 0, v151, vcc
	global_store_dwordx4 v[26:27], v[36:39], off
	global_store_dwordx4 v[24:25], v[32:35], off offset:16
	global_store_dwordx4 v[24:25], v[12:15], off offset:512
	global_store_dwordx4 v[24:25], v[8:11], off offset:528
	s_mov_b64 s[2:3], 0x2c000
	s_nop 0
	v_add_co_u32_e32 v10, vcc, 0x2c000, v150
	v_lshl_add_u64 v[8:9], v[150:151], 0, s[2:3]
	s_nop 0
	v_addc_co_u32_e32 v11, vcc, 0, v151, vcc
	global_store_dwordx4 v[10:11], v[20:23], off
	global_store_dwordx4 v[8:9], v[16:19], off offset:16
	global_store_dwordx4 v[8:9], v[4:7], off offset:512
	global_store_dwordx4 v[8:9], v[0:3], off offset:528
	s_andn2_b64 vcc, exec, s[0:1]
	s_mov_b64 s[0:1], -1
	s_cbranch_vccnz .LBB0_184

; __device__ __forceinline__ float bflo(unsigned u) { return __uint_as_float(u << 16); }
; __device__ __forceinline__ float bfhi(unsigned u) { return __uint_as_float(u & 0xffff0000u); }
; __device__ __forceinline__ void p2_qknorm_row(const Args& a, int row, int lane) {
;     bf16* zb = (bf16*)(a.ws + WS_ZB) + (size_t)row * 5120;
; #pragma unroll
;     for (int part = 0; part < 2; ++part) {
;         v4u* p = (v4u*)(zb + part * 1024 + lane * 16); const v4u u0 = p[0], u1 = p[1];
;         float x[16];
; #pragma unroll
;         for (int e = 0; e < 4; ++e) { x[2 * e] = bflo(u0[e]); x[2 * e + 1] = bfhi(u0[e]); x[8 + 2 * e] = bflo(u1[e]); x[8 + 2 * e + 1] = bfhi(u1[e]); }
;         float ss = 0.f;
; #pragma unroll
;         for (int e = 0; e < 16; ++e) ss += x[e] * x[e];
;         ss = quad_sum(ss);
;         const float rstd = (1.f / sqrtf(ss * (1.f / 64.f) + RMS_EPS)) * (part == 0 ? attn_body::C2 : 1.f);
;         const f32x4* g4 = (const f32x4*)(a.in[part == 0 ? 19 : 20] + (lane & 3) * 16);
; __global__ void __launch_bounds__(NTHR, 2) hybrid_fwd(Args args) {
;     ...
;     {   for (int g = blockIdx.x; g < T / 64; g += F.G) p2b_fgroup(F, args, g);
;         for (int m = F.gw; m < M; m += F.NGW) p2_qknorm_row(args, m, F.lane);
.LBB0_317:
	s_cmp_eq_u32 s98, 5
	s_cbranch_scc1 .Lfg_late_done
	v_cndmask_b32_e64 v0, 0, 1, s[10:11]
	v_cmp_ne_u32_e64 s[0:1], 1, v0
	s_andn2_b64 vcc, exec, s[10:11]
	v_lshlrev_b32_e32 v0, 4, v10
	v_writelane_b32 v254, s0, 39
	s_nop 1
	v_writelane_b32 v254, s1, 40
	s_nop 0
	v_readlane_b32 s10, v254, 26
	v_readlane_b32 s11, v254, 27
	s_branch .LBB0_320
	s_mul_i32 s0, s64, 0x2800
	s_mul_hi_i32 s1, s64, 0x2800
	s_add_u32 s0, s90, s0
	v_ashrrev_i32_e32 v1, 31, v0
	v_lshlrev_b32_e32 v2, 6, v10
	v_readlane_b32 s16, v254, 6
	s_addc_u32 s1, s91, s1
	v_and_b32_e32 v4, 0xc0, v2
	v_mov_b32_e32 v5, 0
	v_readlane_b32 s22, v254, 12
	v_readlane_b32 s23, v254, 13
	v_readlane_b32 s24, v254, 14
	v_readlane_b32 s25, v254, 15
	v_lshl_add_u64 v[6:7], v[0:1], 1, s[0:1]
	s_mov_b64 s[0:1], 0xf000000
	v_lshl_add_u64 v[2:3], s[22:23], 0, v[4:5]
	v_lshl_add_u64 v[4:5], s[24:25], 0, v[4:5]
	v_lshl_add_u64 v[6:7], v[6:7], 0, s[0:1]
	s_mul_hi_i32 s1, s10, 0x2800
	s_mul_i32 s0, s10, 0x2800
	v_mov_b32_e32 v1, 0x358637bd
	s_mov_b32 s2, 0xf800000
	v_mov_b32_e32 v12, 0x260
	s_mov_b32 s3, s64
	v_readlane_b32 s17, v254, 7
	v_readlane_b32 s18, v254, 8
	v_readlane_b32 s19, v254, 9
	v_readlane_b32 s20, v254, 10
	v_readlane_b32 s21, v254, 11
	v_readlane_b32 s26, v254, 16
	v_readlane_b32 s27, v254, 17
	v_readlane_b32 s28, v254, 18
	v_readlane_b32 s29, v254, 19
	v_readlane_b32 s30, v254, 20
	v_readlane_b32 s31, v254, 21
